# HGRN pass-1 item: own v-row loads issued before the next item's k prefetch; counted waits leave the prefetch outstanding
# speedup vs baseline: 1.0042x; 1.0042x over previous
; #define MFMA16(a, b, c) __builtin_amdgcn_mfma_f32_16x16x32_bf16(a, b, c, 0, 0, 0)
; DEV void hg_load_k(const u16* __restrict__ zb, int tid, u16 (&kr)[16]) {
;   const int wid = tid >> 6, lane = tid & 63, dir = wid >> 2, qu = wid & 3;
;   const u16* kp = zb + (long)(qu * 16) * NINP + C_HF + dir * 512 + lane;
; #pragma unroll
;   for (int i = 0; i < 16; ++i) kr[i] = kp[(long)i * NINP];
; }
; DEV void hg_load_v(const u16* __restrict__ zb, int wid, int lane, u16 (&vr)[8]) {
;   const u16* vp = zb + (long)(wid * 8) * NINP + C_HI + lane;
; #pragma unroll
;   for (int i = 0; i < 8; ++i) vr[i] = vp[(long)i * NINP];
; DEV void hg1_item(const Params& p, int item, char* smem, int tid, const u16 (&kr)[16]) {
;     ...
; #pragma unroll
;   for (int ks = 0; ks < 2; ++ks) {
;     const int ao = dir * 9216 + (qu * 16 + fr) * HROW + ks * 64 + fq * 16;
;     const bf16x8 ah = *(const bf16x8*)(smem + H_KH + ao);
; #pragma unroll
;     for (int vt = 0; vt < 4; ++vt) {
;       const bf16x8 b = *(const bf16x8*)(smem + H_VT + (vt * 16 + fr) * HROW + ks * 64 + fq * 16);
;       acc[vt] = MFMA16(ah, b, acc[vt]);
;     }
;   }
;   u16* so = p.Sloc + slot * 4096;
; #pragma unroll
;   for (int vt = 0; vt < 4; ++vt) {
;     uint2 o2;
;     o2.x = pack2(acc[vt][0], acc[vt][1]);
;     o2.y = pack2(acc[vt][2], acc[vt][3]);
;     *(uint2*)(so + (vt * 16 + fr) * 64 + qu * 16 + fq * 4) = o2;
;   }
.LBB0_733:
	s_or_b64 exec, exec, s[8:9]
	s_waitcnt lgkmcnt(0)
	s_barrier
	ds_read_b128 v[2:5], v63 offset:36864
	ds_read_b128 v[6:9], v64
	ds_read_b128 v[10:13], v64 offset:2304
	ds_read_b128 v[14:17], v64 offset:4608
	ds_read_b128 v[18:21], v64 offset:6912
	s_waitcnt lgkmcnt(3)
	v_mfma_f32_16x16x32_bf16 v[6:9], v[2:5], v[6:9], 0
	v_lshlrev_b64 v[0:1], 13, v[0:1]
	v_lshl_add_u64 v[0:1], v[38:39], 0, v[0:1]
	s_mov_b32 s8, 0x5040100
	s_waitcnt lgkmcnt(2)
	v_mfma_f32_16x16x32_bf16 v[10:13], v[2:5], v[10:13], 0
	s_waitcnt lgkmcnt(1)
	v_mfma_f32_16x16x32_bf16 v[14:17], v[2:5], v[14:17], 0
	s_waitcnt lgkmcnt(0)
	v_mfma_f32_16x16x32_bf16 v[2:5], v[2:5], v[18:21], 0
	ds_read_b128 v[18:21], v63 offset:36928
	ds_read_b128 v[22:25], v64 offset:64
	s_waitcnt lgkmcnt(0)
	v_mfma_f32_16x16x32_bf16 v[6:9], v[18:21], v[22:25], v[6:9]
	ds_read_b128 v[22:25], v64 offset:2368
	s_waitcnt lgkmcnt(0)
	v_mfma_f32_16x16x32_bf16 v[10:13], v[18:21], v[22:25], v[10:13]
	ds_read_b128 v[22:25], v64 offset:4672
	s_nop 3
	v_cvt_pk_bf16_f32 v6, v6, v7
	v_cvt_pk_bf16_f32 v7, v8, v9
	s_waitcnt lgkmcnt(0)
	v_mfma_f32_16x16x32_bf16 v[14:17], v[18:21], v[22:25], v[14:17]
	ds_read_b128 v[22:25], v64 offset:6976
	global_store_dwordx2 v[0:1], v[6:7], off
	v_cvt_pk_bf16_f32 v6, v10, v11
	s_waitcnt lgkmcnt(0)
	v_mfma_f32_16x16x32_bf16 v[2:5], v[18:21], v[22:25], v[2:5]
	v_cvt_pk_bf16_f32 v7, v12, v13
	global_store_dwordx2 v[0:1], v[6:7], off offset:2048
	v_add_co_u32_e32 v0, vcc, s71, v0
	v_cvt_pk_bf16_f32 v6, v14, v15
	v_cvt_pk_bf16_f32 v7, v16, v17
	v_addc_co_u32_e32 v1, vcc, 0, v1, vcc
	s_nop 1
	v_cvt_pk_bf16_f32 v2, v2, v3
	v_cvt_pk_bf16_f32 v3, v4, v5
	global_store_dwordx2 v[0:1], v[6:7], off
	global_store_dwordx2 v[0:1], v[2:3], off offset:2048
	s_waitcnt vmcnt(4)
	v_perm_b32 v1, v80, v79, s8
	v_perm_b32 v2, v78, v77, s8
	v_perm_b32 v3, v76, v75, s8
	v_perm_b32 v4, v74, v73, s8
	v_perm_b32 v5, v72, v71, s8
	v_perm_b32 v6, v70, v69, s8
	v_perm_b32 v7, v68, v67, s8
	v_perm_b32 v0, v66, v65, s8
	s_and_b64 vcc, exec, s[6:7]
	s_cbranch_vccnz .LBB0_744
.LBB0_734:
	v_readlane_b32 s6, v253, 2
	s_mov_b32 s11, s10
	s_add_i32 s10, s10, s6
	v_readlane_b32 s7, v253, 3
	s_cmpk_gt_i32 s10, 0x8ff
	s_cselect_b64 s[6:7], -1, 0
	s_cmpk_lt_i32 s10, 0x900
	s_cselect_b32 s8, s10, s11
	s_mov_b32 s50, s8
	s_mov_b32 s19, 0x9000
	s_mov_b32 s18, 0xd000
	s_mov_b32 s17, 0x11000
	s_mov_b32 s16, 0x1e000
	s_ashr_i32 s9, s11, 3
	s_and_b32 s8, s11, 7
	s_mul_hi_i32 s11, s9, 0x38e38e39
	s_lshr_b32 s12, s11, 31
	s_ashr_i32 s11, s11, 3
	s_add_i32 s11, s11, s12
	s_lshl_b32 s12, s11, 3
	s_or_b32 s8, s12, s8
	s_mul_i32 s11, s11, 36
	s_mul_i32 s8, s8, 36
	s_sub_i32 s9, s9, s11
	s_add_i32 s8, s8, s9
	s_mul_hi_i32 s9, s8, 0x38e38e39
	s_lshr_b32 s11, s9, 31
	s_ashr_i32 s9, s9, 3
	s_add_i32 s11, s9, s11
	s_mul_i32 s9, s11, 36
	s_sub_i32 s12, s8, s9
	s_ashr_i32 s8, s11, 3
	s_lshl_b32 s13, s12, 6
	s_mul_hi_i32 s9, s8, 0x900
	s_mulk_i32 s8, 0x900
	s_ashr_i32 s15, s13, 31
	s_add_u32 s8, s8, s13
	s_addc_u32 s9, s9, s15
	s_mulk_i32 s9, 0x4400
	s_mul_hi_u32 s13, s8, 0x4400
	s_add_i32 s13, s13, s9
	s_mulk_i32 s8, 0x4400
	s_add_u32 s8, s88, s8
	s_addc_u32 s9, s89, s13
	s_lshl_b32 s13, s11, 7
	s_and_b32 s13, s13, 0x380
	s_add_u32 s8, s8, s13
	s_addc_u32 s9, s9, 0
	v_mov_b32_e32 v41, v157
	v_lshl_add_u64 v[8:9], s[8:9], 0, v[34:35]
	v_lshl_add_u64 v[8:9], v[8:9], 0, v[40:41]
	v_add_co_u32_e32 v10, vcc, s69, v8
	s_mov_b32 s8, 0x15000
	s_nop 0
	v_addc_co_u32_e32 v11, vcc, 0, v9, vcc
	v_add_co_u32_e32 v12, vcc, s19, v8
	v_lshlrev_b32_e32 v56, 16, v7
	s_nop 0
	v_addc_co_u32_e32 v13, vcc, 0, v9, vcc
	v_add_co_u32_e32 v14, vcc, s18, v8
	v_and_b32_e32 v57, 0xffff0000, v7
	s_nop 0
	v_addc_co_u32_e32 v15, vcc, 0, v9, vcc
	v_add_co_u32_e32 v16, vcc, s17, v8
	v_sub_f32_e32 v7, 1.0, v56
	s_nop 0
	v_addc_co_u32_e32 v17, vcc, 0, v9, vcc
	v_add_co_u32_e32 v18, vcc, s8, v8
	v_log_f32_e32 v7, v7
	s_nop 0
	v_addc_co_u32_e32 v19, vcc, 0, v9, vcc
	v_add_co_u32_e32 v20, vcc, s73, v8
	v_lshlrev_b32_e32 v46, 16, v6
	s_nop 0
	v_addc_co_u32_e32 v21, vcc, 0, v9, vcc
	v_add_co_u32_e32 v22, vcc, s16, v8
	v_and_b32_e32 v47, 0xffff0000, v6
	s_nop 0
	v_addc_co_u32_e32 v23, vcc, 0, v9, vcc
	global_load_ushort v41, v[8:9], off offset:2880
	global_load_ushort v81, v[10:11], off offset:3904
	global_load_ushort v82, v[12:13], off offset:832
	global_load_ushort v83, v[14:15], off offset:1856
	global_load_ushort v84, v[16:17], off offset:2880
	global_load_ushort v85, v[18:19], off offset:3904
	global_load_ushort v86, v[20:21], off offset:832
	global_load_ushort v87, v[22:23], off offset:1856
	s_mov_b32 s8, s50
	s_and_b32 s9, s8, 7
	s_ashr_i32 s8, s8, 3
	s_mul_hi_i32 s51, s8, 0x38e38e39
	s_lshr_b32 s13, s51, 31
	s_ashr_i32 s51, s51, 3
	s_add_i32 s51, s51, s13
	s_lshl_b32 s13, s51, 3
	s_or_b32 s9, s13, s9
	s_mul_i32 s51, s51, 36
	s_mul_i32 s9, s9, 36
	s_sub_i32 s8, s8, s51
	s_add_i32 s9, s9, s8
	s_mul_hi_i32 s8, s9, 0x38e38e39
	s_lshr_b32 s51, s8, 31
	s_ashr_i32 s8, s8, 3
	s_add_i32 s8, s8, s51
	s_mul_i32 s51, s8, 36
	s_sub_i32 s9, s9, s51
	s_ashr_i32 s51, s8, 3
	s_lshl_b32 s9, s9, 6
	s_mul_hi_i32 s13, s51, 0x900
	s_mulk_i32 s51, 0x900
	s_ashr_i32 s15, s9, 31
	s_add_u32 s9, s51, s9
	s_addc_u32 s51, s13, s15
	s_mulk_i32 s51, 0x4400
	s_mul_hi_u32 s13, s9, 0x4400
	s_add_i32 s13, s13, s51
	s_mulk_i32 s9, 0x4400
	s_add_u32 s9, s88, s9
	s_addc_u32 s51, s89, s13
	s_lshl_b32 s8, s8, 7
	s_and_b32 s8, s8, 0x380
	s_add_u32 s8, s9, s8
	s_addc_u32 s9, s51, 0
	v_lshl_add_u64 v[8:9], s[8:9], 0, v[156:157]
	v_lshl_add_u64 v[8:9], v[32:33], 1, v[8:9]
; DEV float bf2f(u16 h) { return __uint_as_float(((unsigned)h) << 16); }
; DEV float flog(float x) { return __builtin_amdgcn_logf(x) * 0.6931471805599453f; }
; DEV void hg_load_k(const u16* __restrict__ zb, int tid, u16 (&kr)[16]) {
;   const int wid = tid >> 6, lane = tid & 63, dir = wid >> 2, qu = wid & 3;
;   const u16* kp = zb + (long)(qu * 16) * NINP + C_HF + dir * 512 + lane;
; #pragma unroll
;   for (int i = 0; i < 16; ++i) kr[i] = kp[(long)i * NINP];
; }
; DEV void hg_load_v(const u16* __restrict__ zb, int wid, int lane, u16 (&vr)[8]) {
;   const u16* vp = zb + (long)(wid * 8) * NINP + C_HI + lane;
; #pragma unroll
;   for (int i = 0; i < 8; ++i) vr[i] = vp[(long)i * NINP];
; }
; DEV void hg_prep(int dir, int qu, int lane, char* smem, const u16 (&kr)[16], float (&g)[16], float (&kk)[16]) {
; #pragma unroll
;   for (int i = 0; i < 16; ++i) {
;     kk[i] = bf2f(kr[i]);
;     g[i] = fmaxf(flog(1.f - kk[i]), -20.f);
;   }
;   float total;
;   if (dir == 0) {
; #pragma unroll
;     for (int i = 1; i < 16; ++i) g[i] += g[i - 1];
;     total = g[15];
;   } else {
; #pragma unroll
;     for (int i = 14; i >= 0; --i) g[i] += g[i + 1];
	v_mov_b32_e32 v190, v40
	v_mov_b32_e32 v191, v157
	v_lshl_add_u64 v[8:9], v[8:9], 0, v[190:191]
	s_movk_i32 s8, 0x5000
	v_add_co_u32_e32 v10, vcc, s8, v8
	s_mov_b32 s19, 0x9000
	s_nop 0
	v_addc_co_u32_e32 v11, vcc, 0, v9, vcc
	v_add_co_u32_e32 v12, vcc, s19, v8
	s_mov_b32 s18, 0xd000
	s_nop 0
	v_addc_co_u32_e32 v13, vcc, 0, v9, vcc
	v_add_co_u32_e32 v14, vcc, s18, v8
	s_mov_b32 s17, 0x11000
	s_nop 0
	v_addc_co_u32_e32 v15, vcc, 0, v9, vcc
	v_add_co_u32_e32 v16, vcc, s17, v8
	s_mov_b32 s16, 0x1e000
	s_nop 0
	v_addc_co_u32_e32 v17, vcc, 0, v9, vcc
	v_add_co_u32_e32 v18, vcc, s68, v8
	s_mov_b32 s8, 0x22000
	s_nop 0
	v_addc_co_u32_e32 v19, vcc, 0, v9, vcc
	v_add_co_u32_e32 v20, vcc, s73, v8
	s_nop 0
	v_addc_co_u32_e32 v21, vcc, 0, v9, vcc
	v_add_co_u32_e32 v22, vcc, s16, v8
	v_and_b32_e32 v49, 0xffff0000, v0
	s_nop 0
	v_addc_co_u32_e32 v23, vcc, 0, v9, vcc
	global_load_ushort v65, v[8:9], off offset:3904
	global_load_ushort v66, v[10:11], off offset:832
	global_load_ushort v67, v[12:13], off offset:1856
	global_load_ushort v68, v[14:15], off offset:2880
	global_load_ushort v69, v[16:17], off offset:3904
	global_load_ushort v70, v[18:19], off offset:832
	global_load_ushort v71, v[20:21], off offset:1856
	global_load_ushort v72, v[22:23], off offset:2880
	v_add_co_u32_e32 v10, vcc, s8, v8
	s_mov_b32 s8, 0x27000
	s_nop 0
	v_addc_co_u32_e32 v11, vcc, 0, v9, vcc
	v_add_co_u32_e32 v12, vcc, s8, v8
	s_mov_b32 s8, 0x2b000
	s_nop 0
	v_addc_co_u32_e32 v13, vcc, 0, v9, vcc
	v_add_co_u32_e32 v14, vcc, s8, v8
	s_mov_b32 s8, 0x2f000
	s_nop 0
	v_addc_co_u32_e32 v15, vcc, 0, v9, vcc
	v_add_co_u32_e32 v16, vcc, s8, v8
	s_mov_b32 s8, 0x33000
	s_nop 0
	v_addc_co_u32_e32 v17, vcc, 0, v9, vcc
	v_add_co_u32_e32 v18, vcc, s8, v8
	s_mov_b32 s8, 0x38000
	s_nop 0
	v_addc_co_u32_e32 v19, vcc, 0, v9, vcc
	v_add_co_u32_e32 v20, vcc, s8, v8
	s_mov_b32 s8, 0x3c000
	s_nop 0
	v_addc_co_u32_e32 v21, vcc, 0, v9, vcc
	v_add_co_u32_e32 v22, vcc, s8, v8
	s_mov_b32 s8, 0x40000
	s_nop 0
	v_addc_co_u32_e32 v23, vcc, 0, v9, vcc
	v_add_co_u32_e32 v8, vcc, s8, v8
	v_addc_co_u32_e32 v9, vcc, 0, v9, vcc
	global_load_ushort v73, v[10:11], off offset:3904
	global_load_ushort v74, v[12:13], off offset:832
	global_load_ushort v75, v[14:15], off offset:1856
	global_load_ushort v76, v[16:17], off offset:2880
	global_load_ushort v77, v[18:19], off offset:3904
	global_load_ushort v78, v[20:21], off offset:832
	global_load_ushort v79, v[22:23], off offset:1856
	global_load_ushort v80, v[8:9], off offset:2880
	v_sub_f32_e32 v8, 1.0, v49
	v_log_f32_e32 v8, v8
	v_sub_f32_e32 v9, 1.0, v57
	v_log_f32_e32 v9, v9
	v_sub_f32_e32 v6, 1.0, v46
	v_mul_f32_e32 v8, 0x3f317218, v8
	v_max_f32_e32 v88, 0xc1a00000, v8
	v_log_f32_e32 v6, v6
	v_sub_f32_e32 v8, 1.0, v47
	v_log_f32_e32 v8, v8
	v_mul_f32_e32 v7, 0x3f317218, v7
	v_lshlrev_b32_e32 v54, 16, v5
	v_max_f32_e32 v89, 0xc1a00000, v7
	v_mul_f32_e32 v7, 0x3f317218, v9
	v_and_b32_e32 v55, 0xffff0000, v5
	v_sub_f32_e32 v5, 1.0, v54
	v_max_f32_e32 v90, 0xc1a00000, v7
	v_mul_f32_e32 v6, 0x3f317218, v6
	v_log_f32_e32 v7, v5
	v_sub_f32_e32 v5, 1.0, v55
	v_max_f32_e32 v91, 0xc1a00000, v6
	v_mul_f32_e32 v6, 0x3f317218, v8
	v_log_f32_e32 v8, v5
	v_lshlrev_b32_e32 v44, 16, v4
	v_and_b32_e32 v45, 0xffff0000, v4
	v_sub_f32_e32 v4, 1.0, v44
	v_max_f32_e32 v5, 0xc1a00000, v6
	v_mul_f32_e32 v6, 0x3f317218, v7
	v_mul_f32_e32 v7, 0x3f317218, v8
	v_log_f32_e32 v4, v4
	v_sub_f32_e32 v8, 1.0, v45
	v_log_f32_e32 v9, v8
	v_lshlrev_b32_e32 v52, 16, v3
	v_mul_f32_e32 v4, 0x3f317218, v4
	v_and_b32_e32 v53, 0xffff0000, v3
	v_sub_f32_e32 v3, 1.0, v52
	v_max_f32_e32 v8, 0xc1a00000, v4
	v_mul_f32_e32 v4, 0x3f317218, v9
	v_log_f32_e32 v3, v3
	v_sub_f32_e32 v9, 1.0, v53
	v_log_f32_e32 v11, v9
	v_lshlrev_b32_e32 v42, 16, v2
	v_mul_f32_e32 v3, 0x3f317218, v3
	v_lshlrev_b32_e32 v50, 16, v1
	v_lshlrev_b32_e32 v48, 16, v0
	v_max_f32_e32 v10, 0xc1a00000, v3
	v_mul_f32_e32 v3, 0x3f317218, v11
	v_and_b32_e32 v43, 0xffff0000, v2
	v_sub_f32_e32 v2, 1.0, v42
	v_and_b32_e32 v51, 0xffff0000, v1
	v_sub_f32_e32 v1, 1.0, v50
	v_sub_f32_e32 v0, 1.0, v48
	v_max_f32_e32 v9, 0xc1a00000, v4
	v_log_f32_e32 v2, v2
	v_sub_f32_e32 v4, 1.0, v43
	v_max_f32_e32 v11, 0xc1a00000, v3
	v_log_f32_e32 v1, v1
	v_sub_f32_e32 v3, 1.0, v51
	v_log_f32_e32 v0, v0
	v_log_f32_e32 v4, v4
	v_log_f32_e32 v3, v3
	v_mul_f32_e32 v2, 0x3f317218, v2
	v_mul_f32_e32 v1, 0x3f317218, v1
	v_mul_f32_e32 v0, 0x3f317218, v0
	v_max_f32_e32 v12, 0xc1a00000, v2
	v_mul_f32_e32 v2, 0x3f317218, v4
	v_max_f32_e32 v14, 0xc1a00000, v1
	v_mul_f32_e32 v1, 0x3f317218, v3
	v_max_f32_e32 v0, 0xc1a00000, v0
	v_max_f32_e32 v6, 0xc1a00000, v6
	v_max_f32_e32 v7, 0xc1a00000, v7
	v_max_f32_e32 v13, 0xc1a00000, v2
	v_max_f32_e32 v15, 0xc1a00000, v1
	s_barrier
	s_and_saveexec_b64 s[8:9], s[40:41]
	s_xor_b64 s[8:9], exec, s[8:9]
	s_cbranch_execz .LBB0_736
	v_add_f32_e32 v14, v14, v15
	v_add_f32_e32 v13, v13, v14
	v_add_f32_e32 v12, v12, v13
	v_add_f32_e32 v11, v11, v12
	v_add_f32_e32 v10, v10, v11
	v_add_f32_e32 v9, v9, v10
	v_add_f32_e32 v8, v8, v9
	v_add_f32_e32 v7, v7, v8
	v_add_f32_e32 v6, v6, v7
	v_add_f32_e32 v5, v5, v6
	v_add_f32_e32 v4, v91, v5
	v_add_f32_e32 v3, v90, v4
	v_add_f32_e32 v2, v89, v3
	v_add_f32_e32 v1, v88, v2
	v_add_f32_e32 v0, v0, v1
	v_mov_b64_e32 v[30:31], v[14:15]
	v_mov_b64_e32 v[28:29], v[12:13]
	v_mov_b64_e32 v[26:27], v[10:11]
	v_mov_b64_e32 v[24:25], v[8:9]
	v_mov_b64_e32 v[22:23], v[6:7]
	v_mov_b64_e32 v[20:21], v[4:5]
	v_mov_b64_e32 v[18:19], v[2:3]
	v_mov_b64_e32 v[16:17], v[0:1]

; DEV void hg1_item(const Params& p, int item, char* smem, int tid, const u16 (&kr)[16]) {
;     ...
;   __syncthreads();
;   hg_prep(dir, qu, lane, smem, kr, g, kk);
;   __syncthreads();
;   hg_store_vt(wid, lane, smem, vr);
;   const float* tot = (const float*)(smem + H_TOT) + dir * 256 + lane;
;   const float t0 = tot[0], t1 = tot[64], t2 = tot[128], t3 = tot[192];
;   const float T = (t0 + t1) + (t2 + t3);
;   float off;
;   if (dir == 0) off = (qu > 0 ? t0 : 0.f) + (qu > 1 ? t1 : 0.f) + (qu > 2 ? t2 : 0.f);
;   else off = (qu < 3 ? t3 : 0.f) + (qu < 2 ? t2 : 0.f) + (qu < 1 ? t1 : 0.f);
.LBB0_738:
	s_or_b64 exec, exec, s[8:9]
	s_mov_b32 s8, 0x5040100
	s_waitcnt vmcnt(16)
	v_perm_b32 v5, v87, v86, s8
	v_perm_b32 v4, v85, v84, s8
	v_perm_b32 v3, v83, v82, s8
	v_perm_b32 v2, v81, v41, s8
	ds_write_b32 v59, v0
	s_waitcnt lgkmcnt(0)
	s_barrier
	ds_write_b128 v61, v[2:5]
	ds_read2st64_b32 v[0:1], v60 offset1:1
	ds_read2st64_b32 v[2:3], v60 offset0:2 offset1:3
	s_and_saveexec_b64 s[8:9], s[40:41]
	s_xor_b64 s[8:9], exec, s[8:9]
	s_cbranch_execz .LBB0_740
	s_waitcnt lgkmcnt(0)
	v_cndmask_b32_e64 v4, v3, 0, s[42:43]
	v_cndmask_b32_e64 v5, 0, v2, s[44:45]
	v_add_f32_e32 v4, v5, v4
	v_cndmask_b32_e64 v5, 0, v1, s[46:47]
	v_add_f32_e32 v4, v5, v4
